# add: non-leader workgroups poll the cross-XCD generation word directly (one hop less per grid barrier)
# baseline (speedup 1.0000x reference)
.LBB0_68:
	s_or_b64 exec, exec, s[6:7]
	v_cvt_f32_u32_e32 v4, v2
	s_waitcnt vmcnt(0)
	v_readfirstlane_b32 s4, v3
	v_sub_u32_e32 v3, 0, v2
	v_rcp_iflag_f32_e32 v4, v4
	v_add_u32_e32 v5, s4, v1
	v_mul_f32_e32 v4, 0x4f7ffffe, v4
	v_cvt_u32_f32_e32 v4, v4
	v_mul_lo_u32 v1, v3, v4
	v_mul_hi_u32 v1, v4, v1
	v_add_u32_e32 v1, v4, v1
	v_mul_hi_u32 v1, v5, v1
	v_mul_lo_u32 v3, v1, v2
	v_sub_u32_e32 v3, v5, v3
	v_add_u32_e32 v4, 1, v1
	v_cmp_ge_u32_e32 vcc, v3, v2
	s_nop 1
	v_cndmask_b32_e32 v1, v1, v4, vcc
	v_sub_u32_e32 v4, v3, v2
	v_cndmask_b32_e32 v3, v3, v4, vcc
	v_add_u32_e32 v4, 1, v1
	v_cmp_ge_u32_e32 vcc, v3, v2
	v_add_u32_e32 v3, 1, v5
	s_nop 0
	v_cndmask_b32_e32 v1, v1, v4, vcc
	v_mul_lo_u32 v4, v2, v1
	v_add_u32_e32 v2, v4, v2
	v_cmp_ne_u32_e32 vcc, v3, v2
	s_and_saveexec_b64 s[4:5], vcc
	s_xor_b64 s[4:5], exec, s[4:5]
	s_cbranch_execz .LBB0_82
	s_movk_i32 s6, 0xd40
	s_mov_b32 s7, 0
	s_lshl_b64 s[6:7], s[6:7], 2
	v_readlane_b32 s8, v252, 44
	v_readlane_b32 s9, v252, 45
	s_add_u32 s10, s8, s6
	s_addc_u32 s11, s9, s7
	s_waitcnt lgkmcnt(0)
	v_mov_b32_e32 v0, 0
	buffer_inv sc1
	global_load_dword v2, v0, s[10:11] sc1
	s_waitcnt vmcnt(0)
	v_cmp_eq_u32_e32 vcc, v2, v1
	s_and_saveexec_b64 s[6:7], vcc
	s_cbranch_execz .LBB0_81
	s_load_dwordx4 s[16:19], s[0:1], 0xa0
	s_mov_b32 s15, 1
	s_mov_b64 s[12:13], 0
	s_waitcnt lgkmcnt(0)
	s_add_u32 s8, s18, 0x4200
	s_addc_u32 s9, s19, 0
	s_branch .LBB0_72

.LBB0_406:
	s_or_b64 exec, exec, s[4:5]
	v_cvt_f32_u32_e32 v5, v3
	s_waitcnt vmcnt(0)
	v_readfirstlane_b32 s2, v4
	v_sub_u32_e32 v4, 0, v3
	v_rcp_iflag_f32_e32 v5, v5
	v_add_u32_e32 v6, s2, v0
	v_mul_f32_e32 v5, 0x4f7ffffe, v5
	v_cvt_u32_f32_e32 v5, v5
	v_mul_lo_u32 v0, v4, v5
	v_mul_hi_u32 v0, v5, v0
	v_add_u32_e32 v0, v5, v0
	v_mul_hi_u32 v0, v6, v0
	v_mul_lo_u32 v4, v0, v3
	v_sub_u32_e32 v4, v6, v4
	v_add_u32_e32 v5, 1, v0
	v_cmp_ge_u32_e32 vcc, v4, v3
	s_nop 1
	v_cndmask_b32_e32 v0, v0, v5, vcc
	v_sub_u32_e32 v5, v4, v3
	v_cndmask_b32_e32 v4, v4, v5, vcc
	v_add_u32_e32 v5, 1, v0
	v_cmp_ge_u32_e32 vcc, v4, v3
	v_add_u32_e32 v4, 1, v6
	s_nop 0
	v_cndmask_b32_e32 v0, v0, v5, vcc
	v_mul_lo_u32 v5, v3, v0
	v_add_u32_e32 v3, v5, v3
	v_cmp_ne_u32_e32 vcc, v4, v3
	s_and_saveexec_b64 s[2:3], vcc
	s_xor_b64 s[2:3], exec, s[2:3]
	s_cbranch_execz .LBB0_420
	s_movk_i32 s86, 0xd40
	s_lshl_b64 s[4:5], s[86:87], 2
	v_readlane_b32 s6, v252, 44
	v_readlane_b32 s7, v252, 45
	s_add_u32 s6, s6, s4
	s_addc_u32 s7, s7, s5
	s_waitcnt lgkmcnt(0)
	s_nop 1
	buffer_inv sc1
	global_load_dword v2, v1, s[6:7] sc1
	s_waitcnt vmcnt(0)
	v_cmp_eq_u32_e32 vcc, v2, v0
	s_and_saveexec_b64 s[4:5], vcc
	s_cbranch_execz .LBB0_419
	s_mov_b32 s21, 1
	s_mov_b64 s[8:9], 0
	s_branch .LBB0_410

.LBB0_1268:
	s_or_b64 exec, exec, s[6:7]
	v_cvt_f32_u32_e32 v5, v3
	s_waitcnt vmcnt(0)
	v_readfirstlane_b32 s4, v4
	v_sub_u32_e32 v4, 0, v3
	v_rcp_iflag_f32_e32 v5, v5
	v_add_u32_e32 v6, s4, v0
	v_mul_f32_e32 v5, 0x4f7ffffe, v5
	v_cvt_u32_f32_e32 v5, v5
	v_mul_lo_u32 v0, v4, v5
	v_mul_hi_u32 v0, v5, v0
	v_add_u32_e32 v0, v5, v0
	v_mul_hi_u32 v0, v6, v0
	v_mul_lo_u32 v4, v0, v3
	v_sub_u32_e32 v4, v6, v4
	v_add_u32_e32 v5, 1, v0
	v_cmp_ge_u32_e32 vcc, v4, v3
	s_nop 1
	v_cndmask_b32_e32 v0, v0, v5, vcc
	v_sub_u32_e32 v5, v4, v3
	v_cndmask_b32_e32 v4, v4, v5, vcc
	v_add_u32_e32 v5, 1, v0
	v_cmp_ge_u32_e32 vcc, v4, v3
	v_add_u32_e32 v4, 1, v6
	s_nop 0
	v_cndmask_b32_e32 v0, v0, v5, vcc
	v_mul_lo_u32 v5, v3, v0
	v_add_u32_e32 v3, v5, v3
	v_cmp_ne_u32_e32 vcc, v4, v3
	s_and_saveexec_b64 s[4:5], vcc
	s_xor_b64 s[4:5], exec, s[4:5]
	s_cbranch_execz .LBB0_1282
	s_movk_i32 s86, 0xd40
	s_lshl_b64 s[6:7], s[86:87], 2
	v_readlane_b32 s8, v252, 44
	v_readlane_b32 s9, v252, 45
	s_add_u32 s8, s8, s6
	s_addc_u32 s9, s9, s7
	s_waitcnt lgkmcnt(0)
	s_nop 1
	buffer_inv sc1
	global_load_dword v2, v1, s[8:9] sc1
	s_waitcnt vmcnt(0)
	v_cmp_eq_u32_e32 vcc, v2, v0
	s_and_saveexec_b64 s[6:7], vcc
	s_cbranch_execz .LBB0_1281
	s_mov_b32 s21, 1
	s_mov_b64 s[10:11], 0
	s_branch .LBB0_1272
